# P4 gate epilogues: gate/add loads hoisted and software-pipelined instead of per-store serialized loads; rowpass_init gain loads hoisted
# speedup vs baseline: 1.0305x; 1.0040x over previous
; __device__ __forceinline__ void rowpass_init(const Frame& F, const Params& p) {
;     bf16* A = (bf16*)(p.ws + WS_A);
;     for (int r = F.gw; r < MREAL; r += F.ngw) {
;         const float* src = r < MF ? p.x + (size_t)r * D : p.meta + (size_t)(r - MF) * D;
;         f32x4 v[8]; float ss = 0.f;
; #pragma unroll
;         for (int j = 0; j < 8; ++j) { v[j] = *(const f32x4*)(src + 4 * F.lane + 256 * j); ss += (v[j].x * v[j].x + v[j].y * v[j].y) + (v[j].z * v[j].z + v[j].w * v[j].w); }
;         const float rs = rsqrtf(wave_sum(ss) * (1.f / D) + EPS);
; #pragma unroll
;         for (int j = 0; j < 8; ++j) {
;             const f32x4 g = *(const f32x4*)(p.n_mix_pre + 4 * F.lane + 256 * j);
.LBB0_36:
	s_or_b64 exec, exec, s[0:1]
	s_ashr_i32 s14, s10, 6
	s_lshl_b32 s0, s11, 3
	s_add_i32 s2, s0, s14
	s_lshl_b32 s26, s82, 3
	s_cmpk_gt_i32 s2, 0x400f
	v_mbcnt_lo_u32_b32 v40, -1, 0
	v_lshlrev_b32_e32 v24, 3, v41
	s_cbranch_scc1 .LBB0_41
	v_mbcnt_hi_u32_b32 v0, -1, v40
	v_and_b32_e32 v1, 64, v0
	v_add_u32_e32 v1, 64, v1
	v_xor_b32_e32 v2, 1, v0
	v_cmp_lt_i32_e32 vcc, v2, v1
	v_mov_b32_e32 v27, 0
	v_mov_b32_e32 v25, v27
	v_cndmask_b32_e32 v2, v0, v2, vcc
	v_lshlrev_b32_e32 v43, 2, v2
	v_xor_b32_e32 v2, 2, v0
	v_cmp_lt_i32_e32 vcc, v2, v1
	v_lshlrev_b32_e32 v26, 4, v41
	s_mov_b64 s[4:5], 0x9e00000
	v_cndmask_b32_e32 v2, v0, v2, vcc
	v_lshlrev_b32_e32 v44, 2, v2
	v_xor_b32_e32 v2, 4, v0
	v_cmp_lt_i32_e32 vcc, v2, v1
	v_lshl_add_u64 v[28:29], s[52:53], 0, v[26:27]
	s_ashr_i32 s3, s2, 31
	v_cndmask_b32_e32 v2, v0, v2, vcc
	v_lshlrev_b32_e32 v45, 2, v2
	v_xor_b32_e32 v2, 8, v0
	v_cmp_lt_i32_e32 vcc, v2, v1
	s_ashr_i32 s27, s26, 31
	s_mov_b32 s1, 0
	v_cndmask_b32_e32 v2, v0, v2, vcc
	v_lshlrev_b32_e32 v46, 2, v2
	v_xor_b32_e32 v2, 16, v0
	v_cmp_lt_i32_e32 vcc, v2, v1
	s_movk_i32 s15, 0x1000
	s_mov_b32 s16, 0x800000
	v_cndmask_b32_e32 v2, v0, v2, vcc
	v_lshlrev_b32_e32 v47, 2, v2
	v_xor_b32_e32 v2, 32, v0
	v_cmp_lt_i32_e32 vcc, v2, v1
	s_mov_b64 s[8:9], s[2:3]
	s_nop 0
	v_cndmask_b32_e32 v0, v0, v2, vcc
	v_lshl_add_u64 v[2:3], s[80:81], 0, v[24:25]
	v_lshl_add_u64 v[30:31], v[2:3], 0, s[4:5]
	s_mov_b64 s[4:5], 0x1000
	v_lshl_add_u64 v[32:33], v[28:29], 0, s[4:5]
	s_mov_b64 s[4:5], 0x1400
	v_lshl_add_u64 v[34:35], v[28:29], 0, s[4:5]
	s_mov_b64 s[4:5], 0x1800
	v_lshl_add_u64 v[36:37], v[28:29], 0, s[4:5]
	s_mov_b64 s[4:5], 0x1c00
	v_lshl_add_u64 v[38:39], v[28:29], 0, s[4:5]
	s_lshl_b64 s[4:5], s[2:3], 13
	v_lshlrev_b32_e32 v48, 2, v0
	v_lshlrev_b32_e32 v0, 2, v41
	s_add_u32 s4, s48, s4
	s_addc_u32 s5, s49, s5
	s_lshl_b64 s[6:7], s[26:27], 13
	v_lshlrev_b32_e32 v26, 2, v0
	v_mov_b32_e32 v25, 0x358637bd
	global_load_dwordx4 v[100:103], v[28:29], off offset:1024
	global_load_dwordx4 v[104:107], v[28:29], off offset:2048
	global_load_dwordx4 v[108:111], v[28:29], off offset:3072
	global_load_dwordx4 v[112:115], v[32:33], off
	global_load_dwordx4 v[116:119], v[34:35], off
	global_load_dwordx4 v[120:123], v[36:37], off
	global_load_dwordx4 v[124:127], v[38:39], off
	s_branch .LBB0_39
; __device__ __forceinline__ unsigned cvt_pk_bf16(float lo, float hi) { cvt_f32x2_t v = {lo, hi}; cvt_bf16x2_t b = __builtin_convertvector(v, cvt_bf16x2_t); return __builtin_bit_cast(unsigned, b); }
; __device__ __forceinline__ void rowpass_init(const Frame& F, const Params& p) {
;     ...
;     for (int r = F.gw; r < MREAL; r += F.ngw) {
;         const float* src = r < MF ? p.x + (size_t)r * D : p.meta + (size_t)(r - MF) * D;
;         f32x4 v[8]; float ss = 0.f;
; #pragma unroll
;         for (int j = 0; j < 8; ++j) { v[j] = *(const f32x4*)(src + 4 * F.lane + 256 * j); ss += (v[j].x * v[j].x + v[j].y * v[j].y) + (v[j].z * v[j].z + v[j].w * v[j].w); }
;         const float rs = rsqrtf(wave_sum(ss) * (1.f / D) + EPS);
; #pragma unroll
;         for (int j = 0; j < 8; ++j) {
;             const f32x4 g = *(const f32x4*)(p.n_mix_pre + 4 * F.lane + 256 * j);
;             u32x2 w; w.x = cvt_pk_bf16(v[j].x * rs * g.x, v[j].y * rs * g.y); w.y = cvt_pk_bf16(v[j].z * rs * g.z, v[j].w * rs * g.w);
;             *(u32x2*)(A + (size_t)r * D + 4 * F.lane + 256 * j) = w; }
.LBB0_38:
	global_load_dwordx4 v[20:23], v26, s[12:13]
	global_load_dwordx4 v[0:3], v26, s[12:13] offset:1024
	global_load_dwordx4 v[16:19], v26, s[12:13] offset:2048
	global_load_dwordx4 v[8:11], v26, s[12:13] offset:3072
	v_lshl_add_u64 v[4:5], s[12:13], 0, v[26:27]
	v_add_co_u32_e32 v4, vcc, s15, v4
	s_lshl_b64 s[10:11], s[10:11], 12
	s_nop 0
	v_addc_co_u32_e32 v5, vcc, 0, v5, vcc
	global_load_dwordx4 v[12:15], v[4:5], off offset:1024
	global_load_dwordx4 v[50:53], v[4:5], off
	global_load_dwordx4 v[54:57], v[4:5], off offset:2048
	s_nop 0
	global_load_dwordx4 v[4:7], v[4:5], off offset:3072
	s_nop 0
	global_load_dwordx4 v[58:61], v[28:29], off
	s_add_u32 s8, s8, s26
	s_addc_u32 s9, s9, s27
	s_add_u32 s4, s4, s6
	s_addc_u32 s5, s5, s7
	s_cmpk_lt_i32 s8, 0x4010
	s_waitcnt vmcnt(8)
	v_mov_b32_e32 v64, v21
	s_waitcnt vmcnt(7)
	v_mov_b32_e32 v65, v1
	s_waitcnt vmcnt(6)
	v_pk_mul_f32 v[68:69], v[18:19], v[18:19]
	v_pk_mul_f32 v[70:71], v[16:17], v[16:17]
	v_mov_b32_e32 v72, v23
	v_mov_b32_e32 v73, v3
	v_mov_b32_e32 v62, v20
	v_mov_b32_e32 v63, v0
	v_mov_b32_e32 v66, v22
	v_mov_b32_e32 v67, v2
	v_pk_mov_b32 v[78:79], v[70:71], v[68:69] op_sel:[1,0]
	v_mov_b32_e32 v71, v69
	v_pk_mul_f32 v[64:65], v[64:65], v[64:65]
	v_pk_mul_f32 v[68:69], v[72:73], v[72:73]
	v_pk_fma_f32 v[62:63], v[62:63], v[62:63], v[64:65]
	v_pk_fma_f32 v[64:65], v[66:67], v[66:67], v[68:69]
	s_waitcnt vmcnt(5)
	v_mul_f32_e32 v74, v9, v9
	v_mul_f32_e32 v76, v11, v11
	v_pk_add_f32 v[66:67], v[78:79], v[70:71]
	v_pk_add_f32 v[62:63], v[62:63], v[64:65]
	v_pk_fma_f32 v[72:73], v[8:9], v[8:9], v[74:75] op_sel_hi:[1,1,0]
	v_pk_fma_f32 v[74:75], v[10:11], v[10:11], v[76:77] op_sel_hi:[1,1,0]
	s_waitcnt vmcnt(3)
	v_mul_f32_e32 v81, v51, v51
	v_mul_f32_e32 v82, v50, v50
	v_pk_add_f32 v[66:67], v[66:67], v[66:67] op_sel:[0,1] op_sel_hi:[1,0]
	v_pk_add_f32 v[62:63], v[62:63], v[62:63] op_sel:[0,1] op_sel_hi:[1,0]
	v_pk_mul_f32 v[68:69], v[14:15], v[14:15]
	v_pk_mul_f32 v[70:71], v[12:13], v[12:13]
	v_mul_f32_e32 v73, v52, v52
	v_mul_f32_e32 v75, v53, v53
	v_mov_b32_e32 v67, v81
	v_mov_b32_e32 v63, v82
	v_pk_mov_b32 v[64:65], v[70:71], v[68:69] op_sel:[1,0]
	v_mov_b32_e32 v71, v69
	v_pk_add_f32 v[72:73], v[72:73], v[74:75]
	v_pk_add_f32 v[62:63], v[62:63], v[66:67]
	s_waitcnt vmcnt(2)
	v_mul_f32_e32 v76, v55, v55
	s_waitcnt vmcnt(1)
	v_mul_f32_e32 v79, v6, v6
	v_mul_f32_e32 v78, v57, v57
	v_pk_add_f32 v[64:65], v[64:65], v[70:71]
	v_pk_add_f32 v[62:63], v[62:63], v[72:73]
	v_mul_f32_e32 v80, v7, v7
	v_mul_f32_e32 v83, v5, v5
	v_mul_f32_e32 v84, v4, v4
	v_pk_fma_f32 v[68:69], v[54:55], v[54:55], v[76:77] op_sel_hi:[1,1,0]
	v_pk_fma_f32 v[76:77], v[56:57], v[56:57], v[78:79] op_sel_hi:[1,1,0]
	v_pk_add_f32 v[64:65], v[64:65], v[64:65] op_sel:[0,1] op_sel_hi:[1,0]
	v_pk_add_f32 v[62:63], v[62:63], v[62:63] op_sel:[0,1] op_sel_hi:[1,0]
	v_mov_b32_e32 v69, v79
	v_mov_b32_e32 v77, v80
	v_mov_b32_e32 v65, v83
	v_mov_b32_e32 v63, v84
	v_pk_add_f32 v[68:69], v[68:69], v[76:77]
	v_pk_add_f32 v[62:63], v[62:63], v[64:65]
	s_nop 0
	v_pk_add_f32 v[62:63], v[62:63], v[68:69]
	s_nop 0
	v_add_f32_e32 v49, v62, v63
	ds_bpermute_b32 v62, v43, v49
	s_waitcnt lgkmcnt(0)
	v_add_f32_e32 v49, v49, v62
	ds_bpermute_b32 v62, v44, v49
	s_waitcnt lgkmcnt(0)
	v_add_f32_e32 v49, v49, v62
	ds_bpermute_b32 v62, v45, v49
	s_waitcnt lgkmcnt(0)
	v_add_f32_e32 v49, v49, v62
	ds_bpermute_b32 v62, v46, v49
	s_waitcnt lgkmcnt(0)
	v_add_f32_e32 v49, v49, v62
	ds_bpermute_b32 v62, v47, v49
	s_waitcnt lgkmcnt(0)
	v_add_f32_e32 v49, v49, v62
	ds_bpermute_b32 v62, v48, v49
	s_waitcnt lgkmcnt(0)
	v_add_f32_e32 v49, v49, v62
	v_fmamk_f32 v49, v49, 0x3a000000, v25
	v_mul_f32_e32 v62, 0x4b800000, v49
	v_cmp_gt_f32_e32 vcc, s16, v49
	s_nop 1
	v_cndmask_b32_e32 v49, v49, v62, vcc
	v_rsq_f32_e32 v49, v49
	v_lshl_add_u64 v[62:63], v[30:31], 0, s[10:11]
	v_mul_f32_e32 v64, 0x45800000, v49
	v_cndmask_b32_e32 v64, v49, v64, vcc
	v_pk_mul_f32 v[20:21], v[20:21], v[64:65] op_sel_hi:[1,0]
	v_pk_mul_f32 v[22:23], v[22:23], v[64:65] op_sel_hi:[1,0]
	s_waitcnt vmcnt(0)
	v_pk_mul_f32 v[20:21], v[58:59], v[20:21]
	v_pk_mul_f32 v[22:23], v[60:61], v[22:23]
	v_cvt_pk_bf16_f32 v20, v20, v21
	v_cvt_pk_bf16_f32 v21, v22, v23
	global_store_dwordx2 v[62:63], v[20:21], off
	v_mov_b64_e32 v[20:21], v[100:101]
	v_mov_b64_e32 v[22:23], v[102:103]
	v_pk_mul_f32 v[0:1], v[0:1], v[64:65] op_sel_hi:[1,0]
	v_pk_mul_f32 v[2:3], v[2:3], v[64:65] op_sel_hi:[1,0]
	v_pk_mul_f32 v[16:17], v[16:17], v[64:65] op_sel_hi:[1,0]
	v_pk_mul_f32 v[18:19], v[18:19], v[64:65] op_sel_hi:[1,0]
	v_pk_mul_f32 v[8:9], v[8:9], v[64:65] op_sel_hi:[1,0]
	v_pk_mul_f32 v[10:11], v[10:11], v[64:65] op_sel_hi:[1,0]
	v_pk_mul_f32 v[4:5], v[4:5], v[64:65] op_sel_hi:[1,0]
	v_pk_mul_f32 v[6:7], v[6:7], v[64:65] op_sel_hi:[1,0]
	v_pk_mul_f32 v[0:1], v[20:21], v[0:1]
	v_pk_mul_f32 v[2:3], v[22:23], v[2:3]
	v_cvt_pk_bf16_f32 v0, v0, v1
	v_cvt_pk_bf16_f32 v1, v2, v3
	global_store_dwordx2 v[62:63], v[0:1], off offset:512
	v_mov_b64_e32 v[0:1], v[104:105]
	v_mov_b64_e32 v[2:3], v[106:107]
	v_pk_mul_f32 v[0:1], v[0:1], v[16:17]
	v_pk_mul_f32 v[2:3], v[2:3], v[18:19]
	v_cvt_pk_bf16_f32 v0, v0, v1
	v_cvt_pk_bf16_f32 v1, v2, v3
	global_store_dwordx2 v[62:63], v[0:1], off offset:1024
	v_mov_b64_e32 v[0:1], v[108:109]
	v_mov_b64_e32 v[2:3], v[110:111]
	v_pk_mul_f32 v[0:1], v[0:1], v[8:9]
	v_pk_mul_f32 v[2:3], v[2:3], v[10:11]
	v_cvt_pk_bf16_f32 v0, v0, v1
	v_cvt_pk_bf16_f32 v1, v2, v3
	global_store_dwordx2 v[62:63], v[0:1], off offset:1536
	v_mov_b64_e32 v[0:1], v[112:113]
	v_mov_b64_e32 v[2:3], v[114:115]
	v_pk_mul_f32 v[8:9], v[50:51], v[64:65] op_sel_hi:[1,0]
	v_pk_mul_f32 v[10:11], v[52:53], v[64:65] op_sel_hi:[1,0]
	v_pk_mul_f32 v[0:1], v[0:1], v[8:9]
	v_pk_mul_f32 v[2:3], v[2:3], v[10:11]
	v_cvt_pk_bf16_f32 v0, v0, v1
	v_cvt_pk_bf16_f32 v1, v2, v3
	global_store_dwordx2 v[62:63], v[0:1], off offset:2048
	v_mov_b64_e32 v[0:1], v[116:117]
	v_mov_b64_e32 v[2:3], v[118:119]
	v_pk_mul_f32 v[8:9], v[12:13], v[64:65] op_sel_hi:[1,0]
	v_pk_mul_f32 v[10:11], v[14:15], v[64:65] op_sel_hi:[1,0]
	v_pk_mul_f32 v[0:1], v[0:1], v[8:9]
	v_pk_mul_f32 v[2:3], v[2:3], v[10:11]
	v_cvt_pk_bf16_f32 v0, v0, v1
	v_cvt_pk_bf16_f32 v1, v2, v3
	global_store_dwordx2 v[62:63], v[0:1], off offset:2560
	v_mov_b64_e32 v[0:1], v[120:121]
	v_mov_b64_e32 v[2:3], v[122:123]
	v_pk_mul_f32 v[8:9], v[54:55], v[64:65] op_sel_hi:[1,0]
	v_pk_mul_f32 v[10:11], v[56:57], v[64:65] op_sel_hi:[1,0]
	v_pk_mul_f32 v[0:1], v[8:9], v[0:1]
	v_pk_mul_f32 v[2:3], v[10:11], v[2:3]
	v_cvt_pk_bf16_f32 v0, v0, v1
	v_cvt_pk_bf16_f32 v1, v2, v3
	global_store_dwordx2 v[62:63], v[0:1], off offset:3072
	v_mov_b64_e32 v[0:1], v[124:125]
	v_mov_b64_e32 v[2:3], v[126:127]
	v_pk_mul_f32 v[0:1], v[4:5], v[0:1]
	v_pk_mul_f32 v[2:3], v[6:7], v[2:3]
	v_cvt_pk_bf16_f32 v0, v0, v1
	v_cvt_pk_bf16_f32 v1, v2, v3
	global_store_dwordx2 v[62:63], v[0:1], off offset:3584
	s_cbranch_scc0 .LBB0_41

; __device__ __forceinline__ unsigned cvt_pk_bf16(float lo, float hi) { cvt_f32x2_t v = {lo, hi}; cvt_bf16x2_t b = __builtin_convertvector(v, cvt_bf16x2_t); return __builtin_bit_cast(unsigned, b); }
; __device__ __forceinline__ float bflo(unsigned w) { return __uint_as_float(w << 16); }
; __device__ __forceinline__ float bfhi(unsigned w) { return __uint_as_float(w & 0xffff0000u); }
;     __device__ __forceinline__ void operator()(const acc_t& acc, const pg8::Unit& u, int wr, int wc, int fr, int fq) const {
;         const int row0 = u.pm * 256 + wr * 64 + fr, col0 = u.pn * 256 + wc * 32 + 8 * fq;
; #pragma unroll
;         for (int ai = 0; ai < 2; ++ai)
; #pragma unroll
;             for (int m = 0; m < 4; ++m) { const size_t off = (size_t)(row0 + ai * 128 + m * 16) * D + col0;
; #pragma unroll
;                 for (int bj = 0; bj < 2; ++bj) { const f32x4 v0 = acc[ai][bj][m][0], v1 = acc[ai][bj][m][1];
;                     const u32x4 g = *(const u32x4*)(G + off + bj * 128);
;                     float o[8] = {bflo(g.x) * v0[0], bfhi(g.x) * v0[1], bflo(g.y) * v0[2], bfhi(g.y) * v0[3], bflo(g.z) * v1[0], bfhi(g.z) * v1[1], bflo(g.w) * v1[2], bfhi(g.w) * v1[3]};
;                     if (ADD) { const u32x4 t = *(const u32x4*)(T + off + bj * 128);
;                         o[0] += bflo(t.x); o[1] += bfhi(t.x); o[2] += bflo(t.y); o[3] += bfhi(t.y); o[4] += bflo(t.z); o[5] += bfhi(t.z); o[6] += bflo(t.w); o[7] += bfhi(t.w); }
;                     u32x4 w; w.x = cvt_pk_bf16(o[0], o[1]); w.y = cvt_pk_bf16(o[2], o[3]); w.z = cvt_pk_bf16(o[4], o[5]); w.w = cvt_pk_bf16(o[6], o[7]);
;                     *(u32x4*)(O + off + bj * 128) = w; }
;                 if (m & 1) asm volatile("" ::: "memory"); }
.LBB0_570:
	v_lshl_add_u32 v144, s24, 8, v147
	v_lshl_or_b32 v142, s25, 8, v149
	v_ashrrev_i32_e32 v145, 31, v144
	v_ashrrev_i32_e32 v143, 31, v142
	v_lshlrev_b64 v[140:141], 11, v[144:145]
	v_lshl_add_u64 v[140:141], v[140:141], 0, v[142:143]
	v_lshlrev_b64 v[140:141], 1, v[140:141]
	v_lshl_add_u64 v[156:157], s[8:9], 0, v[140:141]
	global_load_dwordx4 v[172:175], v140, s[8:9]
	global_load_dwordx4 v[176:179], v140, s[8:9] offset:256
	v_add_u32_e32 v200, 0x10000, v140
	global_load_dwordx4 v[180:183], v200, s[8:9]
	global_load_dwordx4 v[184:187], v200, s[8:9] offset:256
	v_add_u32_e32 v200, 0x20000, v140
	global_load_dwordx4 v[188:191], v200, s[8:9]
	global_load_dwordx4 v[192:195], v200, s[8:9] offset:256
	v_add_u32_e32 v200, 0x30000, v140
	global_load_dwordx4 v[196:199], v200, s[8:9]
	global_load_dwordx4 v[204:207], v200, s[8:9] offset:256
	v_add_u32_e32 v200, 0x80000, v140
	global_load_dwordx4 v[208:211], v200, s[8:9]
	global_load_dwordx4 v[212:215], v200, s[8:9] offset:256
	v_add_u32_e32 v200, 0x90000, v140
	global_load_dwordx4 v[216:219], v200, s[8:9]
	global_load_dwordx4 v[220:223], v200, s[8:9] offset:256
	v_add_u32_e32 v200, 0xa0000, v140
	global_load_dwordx4 v[224:227], v200, s[8:9]
	global_load_dwordx4 v[228:231], v200, s[8:9] offset:256
	v_add_u32_e32 v200, 0xb0000, v140
	global_load_dwordx4 v[232:235], v200, s[8:9]
	global_load_dwordx4 v[236:239], v200, s[8:9] offset:256
	s_waitcnt vmcnt(15)
	s_nop 1
	v_mov_b64_e32 v[152:153], v[172:173]
	v_mov_b64_e32 v[154:155], v[174:175]
	s_mov_b64 s[24:25], 0x80000
	s_andn2_b64 vcc, exec, s[0:1]
	v_lshlrev_b32_e32 v158, 16, v152
	v_and_b32_e32 v159, 0xffff0000, v152
	v_lshlrev_b32_e32 v152, 16, v153
	v_and_b32_e32 v153, 0xffff0000, v153
	v_pk_mul_f32 v[128:129], v[128:129], v[152:153]
	v_lshlrev_b32_e32 v152, 16, v154
	v_and_b32_e32 v153, 0xffff0000, v154
	v_pk_mul_f32 v[152:153], v[122:123], v[152:153]
	v_lshlrev_b32_e32 v122, 16, v155
	v_and_b32_e32 v123, 0xffff0000, v155
	v_pk_mul_f32 v[126:127], v[126:127], v[158:159]
	v_pk_mul_f32 v[154:155], v[124:125], v[122:123]
	v_cvt_pk_bf16_f32 v122, v126, v127
	v_cvt_pk_bf16_f32 v123, v128, v129
	v_cvt_pk_bf16_f32 v124, v152, v153
	v_cvt_pk_bf16_f32 v125, v154, v155
	v_lshl_add_u64 v[126:127], s[2:3], 0, v[140:141]
	global_store_dwordx4 v[126:127], v[122:125], off
	s_waitcnt vmcnt(15)
	s_nop 1
	v_mov_b64_e32 v[122:123], v[176:177]
	v_mov_b64_e32 v[124:125], v[178:179]
	v_lshlrev_b32_e32 v128, 16, v122
	v_and_b32_e32 v129, 0xffff0000, v122
	v_lshlrev_b32_e32 v122, 16, v123
	v_and_b32_e32 v123, 0xffff0000, v123
	v_pk_mul_f32 v[120:121], v[120:121], v[122:123]
	v_lshlrev_b32_e32 v122, 16, v124
	v_and_b32_e32 v123, 0xffff0000, v124
	v_pk_mul_f32 v[122:123], v[114:115], v[122:123]
	v_lshlrev_b32_e32 v114, 16, v125
	v_and_b32_e32 v115, 0xffff0000, v125
	v_pk_mul_f32 v[118:119], v[118:119], v[128:129]
	v_pk_mul_f32 v[124:125], v[116:117], v[114:115]
	v_cvt_pk_bf16_f32 v114, v118, v119
	v_cvt_pk_bf16_f32 v115, v120, v121
	v_cvt_pk_bf16_f32 v116, v122, v123
	v_cvt_pk_bf16_f32 v117, v124, v125
	global_store_dwordx4 v[126:127], v[114:117], off offset:256
	s_nop 1
	v_or_b32_e32 v114, 16, v144
	v_ashrrev_i32_e32 v115, 31, v114
	v_lshlrev_b64 v[114:115], 11, v[114:115]
	v_lshl_add_u64 v[114:115], v[114:115], 0, v[142:143]
	v_lshlrev_b64 v[118:119], 1, v[114:115]
	v_lshl_add_u64 v[120:121], s[8:9], 0, v[118:119]
	s_waitcnt vmcnt(15)
	s_nop 1
	v_mov_b64_e32 v[114:115], v[180:181]
	v_mov_b64_e32 v[116:117], v[182:183]
	v_lshlrev_b32_e32 v122, 16, v114
	v_and_b32_e32 v123, 0xffff0000, v114
	v_lshlrev_b32_e32 v114, 16, v115
	v_and_b32_e32 v115, 0xffff0000, v115
	v_pk_mul_f32 v[112:113], v[112:113], v[114:115]
	v_lshlrev_b32_e32 v114, 16, v116
	v_and_b32_e32 v115, 0xffff0000, v116
	v_pk_mul_f32 v[114:115], v[106:107], v[114:115]
	v_lshlrev_b32_e32 v106, 16, v117
	v_and_b32_e32 v107, 0xffff0000, v117
	v_pk_mul_f32 v[110:111], v[110:111], v[122:123]
	v_pk_mul_f32 v[116:117], v[108:109], v[106:107]
	v_cvt_pk_bf16_f32 v106, v110, v111
	v_cvt_pk_bf16_f32 v107, v112, v113
	v_cvt_pk_bf16_f32 v108, v114, v115
	v_cvt_pk_bf16_f32 v109, v116, v117
	v_lshl_add_u64 v[110:111], s[2:3], 0, v[118:119]
	global_store_dwordx4 v[110:111], v[106:109], off
	s_waitcnt vmcnt(15)
	s_nop 1
	v_mov_b64_e32 v[106:107], v[184:185]
	v_mov_b64_e32 v[108:109], v[186:187]
	v_lshlrev_b32_e32 v112, 16, v106
	v_and_b32_e32 v113, 0xffff0000, v106
	v_lshlrev_b32_e32 v106, 16, v107
	v_and_b32_e32 v107, 0xffff0000, v107
	v_pk_mul_f32 v[104:105], v[104:105], v[106:107]
	v_lshlrev_b32_e32 v106, 16, v108
	v_and_b32_e32 v107, 0xffff0000, v108
	v_pk_mul_f32 v[106:107], v[98:99], v[106:107]
	v_lshlrev_b32_e32 v98, 16, v109
	v_and_b32_e32 v99, 0xffff0000, v109
	v_pk_mul_f32 v[102:103], v[102:103], v[112:113]
	v_pk_mul_f32 v[108:109], v[100:101], v[98:99]
	v_cvt_pk_bf16_f32 v98, v102, v103
	v_cvt_pk_bf16_f32 v99, v104, v105
	v_cvt_pk_bf16_f32 v100, v106, v107
	v_cvt_pk_bf16_f32 v101, v108, v109
	global_store_dwordx4 v[110:111], v[98:101], off offset:256
	s_nop 1
	v_or_b32_e32 v98, 32, v144
	v_ashrrev_i32_e32 v99, 31, v98
	v_lshlrev_b64 v[98:99], 11, v[98:99]
	v_lshl_add_u64 v[98:99], v[98:99], 0, v[142:143]
	v_lshlrev_b64 v[102:103], 1, v[98:99]
	v_lshl_add_u64 v[104:105], s[8:9], 0, v[102:103]
	s_waitcnt vmcnt(15)
	s_nop 1
	v_mov_b64_e32 v[98:99], v[188:189]
	v_mov_b64_e32 v[100:101], v[190:191]
	v_lshlrev_b32_e32 v106, 16, v98
	v_and_b32_e32 v107, 0xffff0000, v98
	v_lshlrev_b32_e32 v98, 16, v99
	v_and_b32_e32 v99, 0xffff0000, v99
	v_pk_mul_f32 v[94:95], v[94:95], v[98:99]
	v_lshlrev_b32_e32 v98, 16, v100
	v_and_b32_e32 v99, 0xffff0000, v100
	v_pk_mul_f32 v[98:99], v[88:89], v[98:99]
	v_lshlrev_b32_e32 v88, 16, v101
	v_and_b32_e32 v89, 0xffff0000, v101
	v_pk_mul_f32 v[92:93], v[92:93], v[106:107]
	v_pk_mul_f32 v[100:101], v[90:91], v[88:89]
	v_cvt_pk_bf16_f32 v88, v92, v93
	v_cvt_pk_bf16_f32 v89, v94, v95
	v_cvt_pk_bf16_f32 v90, v98, v99
	v_cvt_pk_bf16_f32 v91, v100, v101
	v_lshl_add_u64 v[92:93], s[2:3], 0, v[102:103]
	global_store_dwordx4 v[92:93], v[88:91], off
	s_waitcnt vmcnt(15)
; __device__ __forceinline__ unsigned cvt_pk_bf16(float lo, float hi) { cvt_f32x2_t v = {lo, hi}; cvt_bf16x2_t b = __builtin_convertvector(v, cvt_bf16x2_t); return __builtin_bit_cast(unsigned, b); }
; __device__ __forceinline__ float bflo(unsigned w) { return __uint_as_float(w << 16); }
; __device__ __forceinline__ float bfhi(unsigned w) { return __uint_as_float(w & 0xffff0000u); }
;     __device__ __forceinline__ void operator()(const acc_t& acc, const pg8::Unit& u, int wr, int wc, int fr, int fq) const {
;         const int row0 = u.pm * 256 + wr * 64 + fr, col0 = u.pn * 256 + wc * 32 + 8 * fq;
; #pragma unroll
;         for (int ai = 0; ai < 2; ++ai)
; #pragma unroll
;             for (int m = 0; m < 4; ++m) { const size_t off = (size_t)(row0 + ai * 128 + m * 16) * D + col0;
; #pragma unroll
;                 for (int bj = 0; bj < 2; ++bj) { const f32x4 v0 = acc[ai][bj][m][0], v1 = acc[ai][bj][m][1];
;                     const u32x4 g = *(const u32x4*)(G + off + bj * 128);
;                     float o[8] = {bflo(g.x) * v0[0], bfhi(g.x) * v0[1], bflo(g.y) * v0[2], bfhi(g.y) * v0[3], bflo(g.z) * v1[0], bfhi(g.z) * v1[1], bflo(g.w) * v1[2], bfhi(g.w) * v1[3]};
;                     if (ADD) { const u32x4 t = *(const u32x4*)(T + off + bj * 128);
;                         o[0] += bflo(t.x); o[1] += bfhi(t.x); o[2] += bflo(t.y); o[3] += bfhi(t.y); o[4] += bflo(t.z); o[5] += bfhi(t.z); o[6] += bflo(t.w); o[7] += bfhi(t.w); }
;                     u32x4 w; w.x = cvt_pk_bf16(o[0], o[1]); w.y = cvt_pk_bf16(o[2], o[3]); w.z = cvt_pk_bf16(o[4], o[5]); w.w = cvt_pk_bf16(o[6], o[7]);
;                     *(u32x4*)(O + off + bj * 128) = w; }
;                 if (m & 1) asm volatile("" ::: "memory"); }
	s_nop 1
	v_mov_b64_e32 v[88:89], v[192:193]
	v_mov_b64_e32 v[90:91], v[194:195]
	v_lshlrev_b32_e32 v94, 16, v88
	v_and_b32_e32 v95, 0xffff0000, v88
	v_lshlrev_b32_e32 v88, 16, v89
	v_and_b32_e32 v89, 0xffff0000, v89
	v_pk_mul_f32 v[86:87], v[86:87], v[88:89]
	v_lshlrev_b32_e32 v88, 16, v90
	v_and_b32_e32 v89, 0xffff0000, v90
	v_pk_mul_f32 v[88:89], v[80:81], v[88:89]
	v_lshlrev_b32_e32 v80, 16, v91
	v_and_b32_e32 v81, 0xffff0000, v91
	v_pk_mul_f32 v[84:85], v[84:85], v[94:95]
	v_pk_mul_f32 v[90:91], v[82:83], v[80:81]
	v_cvt_pk_bf16_f32 v80, v84, v85
	v_cvt_pk_bf16_f32 v81, v86, v87
	v_cvt_pk_bf16_f32 v82, v88, v89
	v_cvt_pk_bf16_f32 v83, v90, v91
	global_store_dwordx4 v[92:93], v[80:83], off offset:256
	s_nop 1
	v_or_b32_e32 v80, 48, v144
	v_ashrrev_i32_e32 v81, 31, v80
	v_lshlrev_b64 v[80:81], 11, v[80:81]
	v_lshl_add_u64 v[80:81], v[80:81], 0, v[142:143]
	v_lshlrev_b64 v[84:85], 1, v[80:81]
	v_lshl_add_u64 v[86:87], s[8:9], 0, v[84:85]
	s_waitcnt vmcnt(15)
	s_nop 1
	v_mov_b64_e32 v[80:81], v[196:197]
	v_mov_b64_e32 v[82:83], v[198:199]
	v_lshlrev_b32_e32 v88, 16, v80
	v_and_b32_e32 v89, 0xffff0000, v80
	v_lshlrev_b32_e32 v80, 16, v81
	v_and_b32_e32 v81, 0xffff0000, v81
	v_pk_mul_f32 v[78:79], v[78:79], v[80:81]
	v_lshlrev_b32_e32 v80, 16, v82
	v_and_b32_e32 v81, 0xffff0000, v82
	v_pk_mul_f32 v[80:81], v[72:73], v[80:81]
	v_lshlrev_b32_e32 v72, 16, v83
	v_and_b32_e32 v73, 0xffff0000, v83
	v_pk_mul_f32 v[76:77], v[76:77], v[88:89]
	v_pk_mul_f32 v[82:83], v[74:75], v[72:73]
	v_cvt_pk_bf16_f32 v72, v76, v77
	v_cvt_pk_bf16_f32 v73, v78, v79
	v_cvt_pk_bf16_f32 v74, v80, v81
	v_cvt_pk_bf16_f32 v75, v82, v83
	v_lshl_add_u64 v[76:77], s[2:3], 0, v[84:85]
	global_store_dwordx4 v[76:77], v[72:75], off
	s_waitcnt vmcnt(15)
	s_nop 1
	v_mov_b64_e32 v[72:73], v[204:205]
	v_mov_b64_e32 v[74:75], v[206:207]
	v_lshlrev_b32_e32 v78, 16, v72
	v_and_b32_e32 v79, 0xffff0000, v72
	v_lshlrev_b32_e32 v72, 16, v73
	v_and_b32_e32 v73, 0xffff0000, v73
	v_pk_mul_f32 v[70:71], v[70:71], v[72:73]
	v_lshlrev_b32_e32 v72, 16, v74
	v_and_b32_e32 v73, 0xffff0000, v74
	v_pk_mul_f32 v[72:73], v[64:65], v[72:73]
	v_lshlrev_b32_e32 v64, 16, v75
	v_and_b32_e32 v65, 0xffff0000, v75
	v_pk_mul_f32 v[68:69], v[68:69], v[78:79]
	v_pk_mul_f32 v[74:75], v[66:67], v[64:65]
	v_cvt_pk_bf16_f32 v64, v68, v69
	v_cvt_pk_bf16_f32 v65, v70, v71
	v_cvt_pk_bf16_f32 v66, v72, v73
	v_cvt_pk_bf16_f32 v67, v74, v75
	global_store_dwordx4 v[76:77], v[64:67], off offset:256
	v_lshl_add_u64 v[68:69], v[140:141], 0, s[24:25]
	v_lshl_add_u64 v[70:71], s[8:9], 0, v[68:69]
	s_waitcnt vmcnt(15)
	s_nop 1
	v_mov_b64_e32 v[64:65], v[208:209]
	v_mov_b64_e32 v[66:67], v[210:211]
	s_mov_b64 s[24:25], 0x90000
	v_lshlrev_b32_e32 v72, 16, v64
	v_and_b32_e32 v73, 0xffff0000, v64
	v_lshlrev_b32_e32 v64, 16, v65
	v_and_b32_e32 v65, 0xffff0000, v65
	v_pk_mul_f32 v[62:63], v[62:63], v[64:65]
	v_lshlrev_b32_e32 v64, 16, v66
	v_and_b32_e32 v65, 0xffff0000, v66
	v_pk_mul_f32 v[64:65], v[56:57], v[64:65]
	v_lshlrev_b32_e32 v56, 16, v67
	v_and_b32_e32 v57, 0xffff0000, v67
	v_pk_mul_f32 v[60:61], v[60:61], v[72:73]
	v_pk_mul_f32 v[66:67], v[58:59], v[56:57]
	v_cvt_pk_bf16_f32 v56, v60, v61
	v_cvt_pk_bf16_f32 v57, v62, v63
	v_cvt_pk_bf16_f32 v58, v64, v65
	v_cvt_pk_bf16_f32 v59, v66, v67
	v_lshl_add_u64 v[60:61], s[2:3], 0, v[68:69]
	global_store_dwordx4 v[60:61], v[56:59], off
	s_waitcnt vmcnt(15)
	s_nop 1
	v_mov_b64_e32 v[56:57], v[212:213]
	v_mov_b64_e32 v[58:59], v[214:215]
	v_lshlrev_b32_e32 v62, 16, v56
	v_and_b32_e32 v63, 0xffff0000, v56
	v_lshlrev_b32_e32 v56, 16, v57
	v_and_b32_e32 v57, 0xffff0000, v57
	v_pk_mul_f32 v[54:55], v[54:55], v[56:57]
	v_lshlrev_b32_e32 v56, 16, v58
	v_and_b32_e32 v57, 0xffff0000, v58
	v_pk_mul_f32 v[56:57], v[48:49], v[56:57]
	v_lshlrev_b32_e32 v48, 16, v59
	v_and_b32_e32 v49, 0xffff0000, v59
	v_pk_mul_f32 v[52:53], v[52:53], v[62:63]
	v_pk_mul_f32 v[58:59], v[50:51], v[48:49]
	v_cvt_pk_bf16_f32 v48, v52, v53
	v_cvt_pk_bf16_f32 v49, v54, v55
	v_cvt_pk_bf16_f32 v50, v56, v57
	v_cvt_pk_bf16_f32 v51, v58, v59
	v_lshl_add_u64 v[52:53], v[140:141], 0, s[24:25]
	global_store_dwordx4 v[60:61], v[48:51], off offset:256
	v_lshl_add_u64 v[54:55], s[8:9], 0, v[52:53]
	s_waitcnt vmcnt(15)
; __device__ __forceinline__ unsigned cvt_pk_bf16(float lo, float hi) { cvt_f32x2_t v = {lo, hi}; cvt_bf16x2_t b = __builtin_convertvector(v, cvt_bf16x2_t); return __builtin_bit_cast(unsigned, b); }
; __device__ __forceinline__ float bflo(unsigned w) { return __uint_as_float(w << 16); }
; __device__ __forceinline__ float bfhi(unsigned w) { return __uint_as_float(w & 0xffff0000u); }
;     __device__ __forceinline__ void operator()(const acc_t& acc, const pg8::Unit& u, int wr, int wc, int fr, int fq) const {
;         const int row0 = u.pm * 256 + wr * 64 + fr, col0 = u.pn * 256 + wc * 32 + 8 * fq;
; #pragma unroll
;         for (int ai = 0; ai < 2; ++ai)
; #pragma unroll
;             for (int m = 0; m < 4; ++m) { const size_t off = (size_t)(row0 + ai * 128 + m * 16) * D + col0;
; #pragma unroll
;                 for (int bj = 0; bj < 2; ++bj) { const f32x4 v0 = acc[ai][bj][m][0], v1 = acc[ai][bj][m][1];
;                     const u32x4 g = *(const u32x4*)(G + off + bj * 128);
;                     float o[8] = {bflo(g.x) * v0[0], bfhi(g.x) * v0[1], bflo(g.y) * v0[2], bfhi(g.y) * v0[3], bflo(g.z) * v1[0], bfhi(g.z) * v1[1], bflo(g.w) * v1[2], bfhi(g.w) * v1[3]};
;                     if (ADD) { const u32x4 t = *(const u32x4*)(T + off + bj * 128);
;                         o[0] += bflo(t.x); o[1] += bfhi(t.x); o[2] += bflo(t.y); o[3] += bfhi(t.y); o[4] += bflo(t.z); o[5] += bfhi(t.z); o[6] += bflo(t.w); o[7] += bfhi(t.w); }
;                     u32x4 w; w.x = cvt_pk_bf16(o[0], o[1]); w.y = cvt_pk_bf16(o[2], o[3]); w.z = cvt_pk_bf16(o[4], o[5]); w.w = cvt_pk_bf16(o[6], o[7]);
;                     *(u32x4*)(O + off + bj * 128) = w; }
;                 if (m & 1) asm volatile("" ::: "memory"); }
	s_nop 1
	v_mov_b64_e32 v[48:49], v[216:217]
	v_mov_b64_e32 v[50:51], v[218:219]
	s_mov_b64 s[24:25], 0xa0000
	v_lshlrev_b32_e32 v56, 16, v48
	v_and_b32_e32 v57, 0xffff0000, v48
	v_lshlrev_b32_e32 v48, 16, v49
	v_and_b32_e32 v49, 0xffff0000, v49
	v_pk_mul_f32 v[46:47], v[46:47], v[48:49]
	v_lshlrev_b32_e32 v48, 16, v50
	v_and_b32_e32 v49, 0xffff0000, v50
	v_pk_mul_f32 v[48:49], v[40:41], v[48:49]
	v_lshlrev_b32_e32 v40, 16, v51
	v_and_b32_e32 v41, 0xffff0000, v51
	v_pk_mul_f32 v[44:45], v[44:45], v[56:57]
	v_pk_mul_f32 v[50:51], v[42:43], v[40:41]
	v_cvt_pk_bf16_f32 v40, v44, v45
	v_cvt_pk_bf16_f32 v41, v46, v47
	v_cvt_pk_bf16_f32 v42, v48, v49
	v_cvt_pk_bf16_f32 v43, v50, v51
	v_lshl_add_u64 v[44:45], s[2:3], 0, v[52:53]
	global_store_dwordx4 v[44:45], v[40:43], off
	s_waitcnt vmcnt(15)
	s_nop 1
	v_mov_b64_e32 v[40:41], v[220:221]
	v_mov_b64_e32 v[42:43], v[222:223]
	v_lshlrev_b32_e32 v46, 16, v40
	v_and_b32_e32 v47, 0xffff0000, v40
	v_lshlrev_b32_e32 v40, 16, v41
	v_and_b32_e32 v41, 0xffff0000, v41
	v_pk_mul_f32 v[38:39], v[38:39], v[40:41]
	v_lshlrev_b32_e32 v40, 16, v42
	v_and_b32_e32 v41, 0xffff0000, v42
	v_pk_mul_f32 v[40:41], v[32:33], v[40:41]
	v_lshlrev_b32_e32 v32, 16, v43
	v_and_b32_e32 v33, 0xffff0000, v43
	v_pk_mul_f32 v[36:37], v[36:37], v[46:47]
	v_pk_mul_f32 v[42:43], v[34:35], v[32:33]
	v_cvt_pk_bf16_f32 v32, v36, v37
	v_cvt_pk_bf16_f32 v33, v38, v39
	v_cvt_pk_bf16_f32 v34, v40, v41
	v_cvt_pk_bf16_f32 v35, v42, v43
	global_store_dwordx4 v[44:45], v[32:35], off offset:256
	v_lshl_add_u64 v[36:37], v[140:141], 0, s[24:25]
	v_lshl_add_u64 v[38:39], s[8:9], 0, v[36:37]
	s_waitcnt vmcnt(15)
	s_nop 1
	v_mov_b64_e32 v[32:33], v[224:225]
	v_mov_b64_e32 v[34:35], v[226:227]
	s_mov_b64 s[24:25], 0xb0000
	v_lshlrev_b32_e32 v40, 16, v32
	v_and_b32_e32 v41, 0xffff0000, v32
	v_lshlrev_b32_e32 v32, 16, v33
	v_and_b32_e32 v33, 0xffff0000, v33
	v_pk_mul_f32 v[30:31], v[30:31], v[32:33]
	v_lshlrev_b32_e32 v32, 16, v34
	v_and_b32_e32 v33, 0xffff0000, v34
	v_pk_mul_f32 v[32:33], v[24:25], v[32:33]
	v_lshlrev_b32_e32 v24, 16, v35
	v_and_b32_e32 v25, 0xffff0000, v35
	v_pk_mul_f32 v[28:29], v[28:29], v[40:41]
	v_pk_mul_f32 v[34:35], v[26:27], v[24:25]
	v_cvt_pk_bf16_f32 v24, v28, v29
	v_cvt_pk_bf16_f32 v25, v30, v31
	v_cvt_pk_bf16_f32 v26, v32, v33
	v_cvt_pk_bf16_f32 v27, v34, v35
	v_lshl_add_u64 v[28:29], s[2:3], 0, v[36:37]
	global_store_dwordx4 v[28:29], v[24:27], off
	s_waitcnt vmcnt(15)
	s_nop 1
	v_mov_b64_e32 v[24:25], v[228:229]
	v_mov_b64_e32 v[26:27], v[230:231]
	v_lshlrev_b32_e32 v30, 16, v24
	v_and_b32_e32 v31, 0xffff0000, v24
	v_lshlrev_b32_e32 v24, 16, v25
	v_and_b32_e32 v25, 0xffff0000, v25
	v_pk_mul_f32 v[22:23], v[22:23], v[24:25]
	v_lshlrev_b32_e32 v24, 16, v26
	v_and_b32_e32 v25, 0xffff0000, v26
	v_pk_mul_f32 v[24:25], v[16:17], v[24:25]
	v_lshlrev_b32_e32 v16, 16, v27
	v_and_b32_e32 v17, 0xffff0000, v27
	v_pk_mul_f32 v[20:21], v[20:21], v[30:31]
	v_pk_mul_f32 v[26:27], v[18:19], v[16:17]
	v_cvt_pk_bf16_f32 v16, v20, v21
	v_cvt_pk_bf16_f32 v17, v22, v23
	v_cvt_pk_bf16_f32 v18, v24, v25
	v_cvt_pk_bf16_f32 v19, v26, v27
	v_lshl_add_u64 v[20:21], v[140:141], 0, s[24:25]
	global_store_dwordx4 v[28:29], v[16:19], off offset:256
	v_lshl_add_u64 v[22:23], s[8:9], 0, v[20:21]
	s_waitcnt vmcnt(15)
	s_nop 1
	v_mov_b64_e32 v[16:17], v[232:233]
	v_mov_b64_e32 v[18:19], v[234:235]
	s_mov_b64 s[24:25], -1
	v_lshlrev_b32_e32 v24, 16, v16
	v_and_b32_e32 v25, 0xffff0000, v16
	v_lshlrev_b32_e32 v16, 16, v17
	v_and_b32_e32 v17, 0xffff0000, v17
	v_pk_mul_f32 v[14:15], v[14:15], v[16:17]
	v_lshlrev_b32_e32 v16, 16, v18
	v_and_b32_e32 v17, 0xffff0000, v18
	v_pk_mul_f32 v[16:17], v[8:9], v[16:17]
	v_lshlrev_b32_e32 v8, 16, v19
	v_and_b32_e32 v9, 0xffff0000, v19
	v_pk_mul_f32 v[12:13], v[12:13], v[24:25]
	v_pk_mul_f32 v[18:19], v[10:11], v[8:9]
	v_cvt_pk_bf16_f32 v8, v12, v13
	v_cvt_pk_bf16_f32 v9, v14, v15
	v_cvt_pk_bf16_f32 v10, v16, v17
	v_cvt_pk_bf16_f32 v11, v18, v19
	v_lshl_add_u64 v[12:13], s[2:3], 0, v[20:21]
	global_store_dwordx4 v[12:13], v[8:11], off
	s_waitcnt vmcnt(15)
	s_nop 1
	v_mov_b64_e32 v[8:9], v[236:237]
	v_mov_b64_e32 v[10:11], v[238:239]
	v_lshlrev_b32_e32 v14, 16, v8
	v_and_b32_e32 v15, 0xffff0000, v8
	v_lshlrev_b32_e32 v8, 16, v9
	v_and_b32_e32 v9, 0xffff0000, v9
	v_pk_mul_f32 v[6:7], v[6:7], v[8:9]
	v_lshlrev_b32_e32 v8, 16, v10
	v_and_b32_e32 v9, 0xffff0000, v10
	v_pk_mul_f32 v[8:9], v[0:1], v[8:9]
	v_lshlrev_b32_e32 v0, 16, v11
	v_and_b32_e32 v1, 0xffff0000, v11
	v_pk_mul_f32 v[4:5], v[4:5], v[14:15]
	v_pk_mul_f32 v[10:11], v[2:3], v[0:1]
	v_cvt_pk_bf16_f32 v0, v4, v5
	v_cvt_pk_bf16_f32 v1, v6, v7
	v_cvt_pk_bf16_f32 v2, v8, v9
	v_cvt_pk_bf16_f32 v3, v10, v11
	global_store_dwordx4 v[12:13], v[0:3], off offset:256
	s_cbranch_vccnz .LBB0_559
	s_andn2_b64 vcc, exec, s[6:7]
	s_cbranch_vccnz .LBB0_558
	s_barrier
	s_branch .LBB0_558

; __device__ __forceinline__ unsigned cvt_pk_bf16(float lo, float hi) { cvt_f32x2_t v = {lo, hi}; cvt_bf16x2_t b = __builtin_convertvector(v, cvt_bf16x2_t); return __builtin_bit_cast(unsigned, b); }
; __device__ __forceinline__ float bflo(unsigned w) { return __uint_as_float(w << 16); }
; __device__ __forceinline__ float bfhi(unsigned w) { return __uint_as_float(w & 0xffff0000u); }
;     __device__ __forceinline__ void operator()(const acc_t& acc, const pg8::Unit& u, int wr, int wc, int fr, int fq) const {
;         const int row0 = u.pm * 256 + wr * 64 + fr, col0 = u.pn * 256 + wc * 32 + 8 * fq;
; #pragma unroll
;         for (int ai = 0; ai < 2; ++ai)
; #pragma unroll
;             for (int m = 0; m < 4; ++m) { const size_t off = (size_t)(row0 + ai * 128 + m * 16) * D + col0;
; #pragma unroll
;                 for (int bj = 0; bj < 2; ++bj) { const f32x4 v0 = acc[ai][bj][m][0], v1 = acc[ai][bj][m][1];
;                     const u32x4 g = *(const u32x4*)(G + off + bj * 128);
;                     float o[8] = {bflo(g.x) * v0[0], bfhi(g.x) * v0[1], bflo(g.y) * v0[2], bfhi(g.y) * v0[3], bflo(g.z) * v1[0], bfhi(g.z) * v1[1], bflo(g.w) * v1[2], bfhi(g.w) * v1[3]};
;                     if (ADD) { const u32x4 t = *(const u32x4*)(T + off + bj * 128);
;                         o[0] += bflo(t.x); o[1] += bfhi(t.x); o[2] += bflo(t.y); o[3] += bfhi(t.y); o[4] += bflo(t.z); o[5] += bfhi(t.z); o[6] += bflo(t.w); o[7] += bfhi(t.w); }
;                     u32x4 w; w.x = cvt_pk_bf16(o[0], o[1]); w.y = cvt_pk_bf16(o[2], o[3]); w.z = cvt_pk_bf16(o[4], o[5]); w.w = cvt_pk_bf16(o[6], o[7]);
;                     *(u32x4*)(O + off + bj * 128) = w; }
;                 if (m & 1) asm volatile("" ::: "memory"); }
.LBB0_635:
	v_lshl_add_u32 v148, s26, 8, v131
	v_lshl_or_b32 v146, s27, 8, v155
	v_ashrrev_i32_e32 v149, 31, v148
	v_ashrrev_i32_e32 v147, 31, v146
	v_lshlrev_b64 v[144:145], 11, v[148:149]
	v_lshl_add_u64 v[144:145], v[144:145], 0, v[146:147]
	v_lshlrev_b64 v[144:145], 1, v[144:145]
	v_lshl_add_u64 v[172:173], s[8:9], 0, v[144:145]
	v_lshl_add_u64 v[174:175], s[2:3], 0, v[144:145]
	global_load_dwordx4 v[180:183], v144, s[8:9]
	global_load_dwordx4 v[216:219], v144, s[2:3]
	global_load_dwordx4 v[184:187], v144, s[8:9] offset:256
	global_load_dwordx4 v[220:223], v144, s[2:3] offset:256
	v_add_u32_e32 v200, 0x10000, v144
	global_load_dwordx4 v[188:191], v200, s[8:9]
	global_load_dwordx4 v[224:227], v200, s[2:3]
	v_add_u32_e32 v200, 0x10000, v144
	global_load_dwordx4 v[192:195], v200, s[8:9] offset:256
	global_load_dwordx4 v[228:231], v200, s[2:3] offset:256
	v_add_u32_e32 v200, 0x20000, v144
	global_load_dwordx4 v[196:199], v200, s[8:9]
	global_load_dwordx4 v[232:235], v200, s[2:3]
	v_add_u32_e32 v200, 0x20000, v144
	global_load_dwordx4 v[204:207], v200, s[8:9] offset:256
	global_load_dwordx4 v[236:239], v200, s[2:3] offset:256
	v_add_u32_e32 v200, 0x30000, v144
	global_load_dwordx4 v[208:211], v200, s[8:9]
	global_load_dwordx4 v[240:243], v200, s[2:3]
	v_add_u32_e32 v200, 0x30000, v144
	global_load_dwordx4 v[212:215], v200, s[8:9] offset:256
	global_load_dwordx4 v[244:247], v200, s[2:3] offset:256
	s_waitcnt vmcnt(14)
	s_nop 1
	v_mov_b64_e32 v[158:159], v[180:181]
	v_mov_b64_e32 v[160:161], v[182:183]
	v_mov_b64_e32 v[162:163], v[216:217]
	v_mov_b64_e32 v[164:165], v[218:219]
	s_mov_b64 s[26:27], 0x80000
	s_andn2_b64 vcc, exec, s[0:1]
	v_lshlrev_b32_e32 v176, 16, v158
	v_and_b32_e32 v177, 0xffff0000, v158
	v_lshlrev_b32_e32 v178, 16, v162
	v_and_b32_e32 v179, 0xffff0000, v162
	v_lshlrev_b32_e32 v158, 16, v159
	v_and_b32_e32 v159, 0xffff0000, v159
	v_lshlrev_b32_e32 v162, 16, v163
	v_and_b32_e32 v163, 0xffff0000, v163
	v_pk_fma_f32 v[128:129], v[128:129], v[158:159], v[162:163]
	v_lshlrev_b32_e32 v158, 16, v160
	v_and_b32_e32 v159, 0xffff0000, v160
	v_lshlrev_b32_e32 v162, 16, v164
	v_and_b32_e32 v163, 0xffff0000, v164
	v_pk_fma_f32 v[158:159], v[122:123], v[158:159], v[162:163]
	v_lshlrev_b32_e32 v122, 16, v161
	v_and_b32_e32 v123, 0xffff0000, v161
	v_lshlrev_b32_e32 v160, 16, v165
	v_and_b32_e32 v161, 0xffff0000, v165
	v_pk_fma_f32 v[126:127], v[126:127], v[176:177], v[178:179]
	v_pk_fma_f32 v[160:161], v[124:125], v[122:123], v[160:161]
	v_cvt_pk_bf16_f32 v122, v126, v127
	v_cvt_pk_bf16_f32 v123, v128, v129
	v_cvt_pk_bf16_f32 v124, v158, v159
	v_cvt_pk_bf16_f32 v125, v160, v161
	v_lshl_add_u64 v[158:159], s[10:11], 0, v[144:145]
	global_store_dwordx4 v[158:159], v[122:125], off
	v_add_u32_e32 v200, 0x80000, v144
	global_load_dwordx4 v[180:183], v200, s[8:9]
	global_load_dwordx4 v[216:219], v200, s[2:3]
	s_waitcnt vmcnt(15)
	s_nop 1
	v_mov_b64_e32 v[122:123], v[184:185]
	v_mov_b64_e32 v[124:125], v[186:187]
	s_nop 0
	v_mov_b64_e32 v[126:127], v[220:221]
	v_mov_b64_e32 v[128:129], v[222:223]
	v_lshlrev_b32_e32 v160, 16, v122
	v_and_b32_e32 v161, 0xffff0000, v122
	v_lshlrev_b32_e32 v162, 16, v126
	v_and_b32_e32 v163, 0xffff0000, v126
	v_lshlrev_b32_e32 v122, 16, v123
	v_and_b32_e32 v123, 0xffff0000, v123
	v_lshlrev_b32_e32 v126, 16, v127
	v_and_b32_e32 v127, 0xffff0000, v127
	v_pk_fma_f32 v[120:121], v[120:121], v[122:123], v[126:127]
	v_lshlrev_b32_e32 v122, 16, v124
	v_and_b32_e32 v123, 0xffff0000, v124
	v_lshlrev_b32_e32 v126, 16, v128
	v_and_b32_e32 v127, 0xffff0000, v128
	v_pk_fma_f32 v[122:123], v[114:115], v[122:123], v[126:127]
	v_lshlrev_b32_e32 v114, 16, v125
	v_and_b32_e32 v115, 0xffff0000, v125
	v_lshlrev_b32_e32 v124, 16, v129
	v_and_b32_e32 v125, 0xffff0000, v129
	v_pk_fma_f32 v[118:119], v[118:119], v[160:161], v[162:163]
	v_pk_fma_f32 v[124:125], v[116:117], v[114:115], v[124:125]
	v_cvt_pk_bf16_f32 v114, v118, v119
	v_cvt_pk_bf16_f32 v115, v120, v121
	v_cvt_pk_bf16_f32 v116, v122, v123
	v_cvt_pk_bf16_f32 v117, v124, v125
	global_store_dwordx4 v[158:159], v[114:117], off offset:256
	v_add_u32_e32 v200, 0x80000, v144
	global_load_dwordx4 v[184:187], v200, s[8:9] offset:256
	global_load_dwordx4 v[220:223], v200, s[2:3] offset:256
	s_nop 1
	v_or_b32_e32 v114, 16, v148
	v_ashrrev_i32_e32 v115, 31, v114
	v_lshlrev_b64 v[114:115], 11, v[114:115]
	v_lshl_add_u64 v[114:115], v[114:115], 0, v[146:147]
	v_lshlrev_b64 v[124:125], 1, v[114:115]
	v_lshl_add_u64 v[114:115], s[8:9], 0, v[124:125]
	v_lshl_add_u64 v[126:127], s[2:3], 0, v[124:125]
	s_waitcnt vmcnt(16)
	s_nop 1
	v_mov_b64_e32 v[116:117], v[188:189]
	v_mov_b64_e32 v[118:119], v[190:191]
	v_mov_b64_e32 v[120:121], v[224:225]
	v_mov_b64_e32 v[122:123], v[226:227]
	v_lshlrev_b32_e32 v128, 16, v116
	v_and_b32_e32 v129, 0xffff0000, v116
	v_lshlrev_b32_e32 v158, 16, v120
	v_and_b32_e32 v159, 0xffff0000, v120
	v_lshlrev_b32_e32 v116, 16, v117
	v_and_b32_e32 v117, 0xffff0000, v117
	v_lshlrev_b32_e32 v120, 16, v121
	v_and_b32_e32 v121, 0xffff0000, v121
	v_pk_fma_f32 v[112:113], v[112:113], v[116:117], v[120:121]
	v_lshlrev_b32_e32 v116, 16, v118
	v_and_b32_e32 v117, 0xffff0000, v118
	v_lshlrev_b32_e32 v120, 16, v122
	v_and_b32_e32 v121, 0xffff0000, v122
	v_pk_fma_f32 v[116:117], v[106:107], v[116:117], v[120:121]
	v_lshlrev_b32_e32 v106, 16, v119
	v_and_b32_e32 v107, 0xffff0000, v119
	v_lshlrev_b32_e32 v118, 16, v123
	v_and_b32_e32 v119, 0xffff0000, v123
	v_pk_fma_f32 v[110:111], v[110:111], v[128:129], v[158:159]
	v_pk_fma_f32 v[118:119], v[108:109], v[106:107], v[118:119]
	v_cvt_pk_bf16_f32 v106, v110, v111
	v_cvt_pk_bf16_f32 v107, v112, v113
	v_cvt_pk_bf16_f32 v108, v116, v117
	v_cvt_pk_bf16_f32 v109, v118, v119
	v_lshl_add_u64 v[116:117], s[10:11], 0, v[124:125]
	global_store_dwordx4 v[116:117], v[106:109], off
	v_add_u32_e32 v200, 0x90000, v144
	global_load_dwordx4 v[188:191], v200, s[8:9]
	global_load_dwordx4 v[224:227], v200, s[2:3]
	s_waitcnt vmcnt(17)
; __device__ __forceinline__ unsigned cvt_pk_bf16(float lo, float hi) { cvt_f32x2_t v = {lo, hi}; cvt_bf16x2_t b = __builtin_convertvector(v, cvt_bf16x2_t); return __builtin_bit_cast(unsigned, b); }
; __device__ __forceinline__ float bflo(unsigned w) { return __uint_as_float(w << 16); }
; __device__ __forceinline__ float bfhi(unsigned w) { return __uint_as_float(w & 0xffff0000u); }
;     __device__ __forceinline__ void operator()(const acc_t& acc, const pg8::Unit& u, int wr, int wc, int fr, int fq) const {
;         const int row0 = u.pm * 256 + wr * 64 + fr, col0 = u.pn * 256 + wc * 32 + 8 * fq;
; #pragma unroll
;         for (int ai = 0; ai < 2; ++ai)
; #pragma unroll
;             for (int m = 0; m < 4; ++m) { const size_t off = (size_t)(row0 + ai * 128 + m * 16) * D + col0;
; #pragma unroll
;                 for (int bj = 0; bj < 2; ++bj) { const f32x4 v0 = acc[ai][bj][m][0], v1 = acc[ai][bj][m][1];
;                     const u32x4 g = *(const u32x4*)(G + off + bj * 128);
;                     float o[8] = {bflo(g.x) * v0[0], bfhi(g.x) * v0[1], bflo(g.y) * v0[2], bfhi(g.y) * v0[3], bflo(g.z) * v1[0], bfhi(g.z) * v1[1], bflo(g.w) * v1[2], bfhi(g.w) * v1[3]};
;                     if (ADD) { const u32x4 t = *(const u32x4*)(T + off + bj * 128);
;                         o[0] += bflo(t.x); o[1] += bfhi(t.x); o[2] += bflo(t.y); o[3] += bfhi(t.y); o[4] += bflo(t.z); o[5] += bfhi(t.z); o[6] += bflo(t.w); o[7] += bfhi(t.w); }
;                     u32x4 w; w.x = cvt_pk_bf16(o[0], o[1]); w.y = cvt_pk_bf16(o[2], o[3]); w.z = cvt_pk_bf16(o[4], o[5]); w.w = cvt_pk_bf16(o[6], o[7]);
;                     *(u32x4*)(O + off + bj * 128) = w; }
;                 if (m & 1) asm volatile("" ::: "memory"); }
	s_nop 1
	v_mov_b64_e32 v[106:107], v[192:193]
	v_mov_b64_e32 v[108:109], v[194:195]
	s_nop 0
	v_mov_b64_e32 v[110:111], v[228:229]
	v_mov_b64_e32 v[112:113], v[230:231]
	v_lshlrev_b32_e32 v114, 16, v106
	v_and_b32_e32 v115, 0xffff0000, v106
	v_lshlrev_b32_e32 v118, 16, v110
	v_and_b32_e32 v119, 0xffff0000, v110
	v_lshlrev_b32_e32 v106, 16, v107
	v_and_b32_e32 v107, 0xffff0000, v107
	v_lshlrev_b32_e32 v110, 16, v111
	v_and_b32_e32 v111, 0xffff0000, v111
	v_pk_fma_f32 v[104:105], v[104:105], v[106:107], v[110:111]
	v_lshlrev_b32_e32 v106, 16, v108
	v_and_b32_e32 v107, 0xffff0000, v108
	v_lshlrev_b32_e32 v110, 16, v112
	v_and_b32_e32 v111, 0xffff0000, v112
	v_pk_fma_f32 v[106:107], v[98:99], v[106:107], v[110:111]
	v_lshlrev_b32_e32 v98, 16, v109
	v_and_b32_e32 v99, 0xffff0000, v109
	v_lshlrev_b32_e32 v108, 16, v113
	v_and_b32_e32 v109, 0xffff0000, v113
	v_pk_fma_f32 v[102:103], v[102:103], v[114:115], v[118:119]
	v_pk_fma_f32 v[108:109], v[100:101], v[98:99], v[108:109]
	v_cvt_pk_bf16_f32 v98, v102, v103
	v_cvt_pk_bf16_f32 v99, v104, v105
	v_cvt_pk_bf16_f32 v100, v106, v107
	v_cvt_pk_bf16_f32 v101, v108, v109
	global_store_dwordx4 v[116:117], v[98:101], off offset:256
	v_add_u32_e32 v200, 0x90000, v144
	global_load_dwordx4 v[192:195], v200, s[8:9] offset:256
	global_load_dwordx4 v[228:231], v200, s[2:3] offset:256
	s_nop 1
	v_or_b32_e32 v98, 32, v148
	v_ashrrev_i32_e32 v99, 31, v98
	v_lshlrev_b64 v[98:99], 11, v[98:99]
	v_lshl_add_u64 v[98:99], v[98:99], 0, v[146:147]
	v_lshlrev_b64 v[108:109], 1, v[98:99]
	v_lshl_add_u64 v[98:99], s[8:9], 0, v[108:109]
	v_lshl_add_u64 v[110:111], s[2:3], 0, v[108:109]
	s_waitcnt vmcnt(18)
	s_nop 1
	v_mov_b64_e32 v[100:101], v[196:197]
	v_mov_b64_e32 v[102:103], v[198:199]
	v_mov_b64_e32 v[104:105], v[232:233]
	v_mov_b64_e32 v[106:107], v[234:235]
	v_lshlrev_b32_e32 v112, 16, v100
	v_and_b32_e32 v113, 0xffff0000, v100
	v_lshlrev_b32_e32 v114, 16, v104
	v_and_b32_e32 v115, 0xffff0000, v104
	v_lshlrev_b32_e32 v100, 16, v101
	v_and_b32_e32 v101, 0xffff0000, v101
	v_lshlrev_b32_e32 v104, 16, v105
	v_and_b32_e32 v105, 0xffff0000, v105
	v_pk_fma_f32 v[94:95], v[94:95], v[100:101], v[104:105]
	v_lshlrev_b32_e32 v100, 16, v102
	v_and_b32_e32 v101, 0xffff0000, v102
	v_lshlrev_b32_e32 v104, 16, v106
	v_and_b32_e32 v105, 0xffff0000, v106
	v_pk_fma_f32 v[100:101], v[88:89], v[100:101], v[104:105]
	v_lshlrev_b32_e32 v88, 16, v103
	v_and_b32_e32 v89, 0xffff0000, v103
	v_lshlrev_b32_e32 v102, 16, v107
	v_and_b32_e32 v103, 0xffff0000, v107
	v_pk_fma_f32 v[92:93], v[92:93], v[112:113], v[114:115]
	v_pk_fma_f32 v[102:103], v[90:91], v[88:89], v[102:103]
	v_cvt_pk_bf16_f32 v88, v92, v93
	v_cvt_pk_bf16_f32 v89, v94, v95
	v_cvt_pk_bf16_f32 v90, v100, v101
	v_cvt_pk_bf16_f32 v91, v102, v103
	v_lshl_add_u64 v[100:101], s[10:11], 0, v[108:109]
	global_store_dwordx4 v[100:101], v[88:91], off
	v_add_u32_e32 v200, 0xa0000, v144
	global_load_dwordx4 v[196:199], v200, s[8:9]
	global_load_dwordx4 v[232:235], v200, s[2:3]
	s_waitcnt vmcnt(19)
	s_nop 1
	v_mov_b64_e32 v[88:89], v[204:205]
	v_mov_b64_e32 v[90:91], v[206:207]
	s_nop 0
	v_mov_b64_e32 v[92:93], v[236:237]
	v_mov_b64_e32 v[94:95], v[238:239]
	v_lshlrev_b32_e32 v98, 16, v88
	v_and_b32_e32 v99, 0xffff0000, v88
	v_lshlrev_b32_e32 v102, 16, v92
	v_and_b32_e32 v103, 0xffff0000, v92
	v_lshlrev_b32_e32 v88, 16, v89
	v_and_b32_e32 v89, 0xffff0000, v89
	v_lshlrev_b32_e32 v92, 16, v93
	v_and_b32_e32 v93, 0xffff0000, v93
	v_pk_fma_f32 v[86:87], v[86:87], v[88:89], v[92:93]
	v_lshlrev_b32_e32 v88, 16, v90
	v_and_b32_e32 v89, 0xffff0000, v90
	v_lshlrev_b32_e32 v92, 16, v94
	v_and_b32_e32 v93, 0xffff0000, v94
	v_pk_fma_f32 v[88:89], v[80:81], v[88:89], v[92:93]
	v_lshlrev_b32_e32 v80, 16, v91
	v_and_b32_e32 v81, 0xffff0000, v91
	v_lshlrev_b32_e32 v90, 16, v95
	v_and_b32_e32 v91, 0xffff0000, v95
	v_pk_fma_f32 v[84:85], v[84:85], v[98:99], v[102:103]
	v_pk_fma_f32 v[90:91], v[82:83], v[80:81], v[90:91]
	v_cvt_pk_bf16_f32 v80, v84, v85
	v_cvt_pk_bf16_f32 v81, v86, v87
	v_cvt_pk_bf16_f32 v82, v88, v89
	v_cvt_pk_bf16_f32 v83, v90, v91
	global_store_dwordx4 v[100:101], v[80:83], off offset:256
	v_add_u32_e32 v200, 0xa0000, v144
	global_load_dwordx4 v[204:207], v200, s[8:9] offset:256
	global_load_dwordx4 v[236:239], v200, s[2:3] offset:256
	s_nop 1
	v_or_b32_e32 v80, 48, v148
	v_ashrrev_i32_e32 v81, 31, v80
	v_lshlrev_b64 v[80:81], 11, v[80:81]
	v_lshl_add_u64 v[80:81], v[80:81], 0, v[146:147]
	v_lshlrev_b64 v[90:91], 1, v[80:81]
	v_lshl_add_u64 v[80:81], s[8:9], 0, v[90:91]
	v_lshl_add_u64 v[92:93], s[2:3], 0, v[90:91]
	s_waitcnt vmcnt(20)
	s_nop 1
	v_mov_b64_e32 v[82:83], v[208:209]
	v_mov_b64_e32 v[84:85], v[210:211]
	v_mov_b64_e32 v[86:87], v[240:241]
	v_mov_b64_e32 v[88:89], v[242:243]
	v_lshlrev_b32_e32 v94, 16, v82
	v_and_b32_e32 v95, 0xffff0000, v82
	v_lshlrev_b32_e32 v98, 16, v86
	v_and_b32_e32 v99, 0xffff0000, v86
	v_lshlrev_b32_e32 v82, 16, v83
	v_and_b32_e32 v83, 0xffff0000, v83
	v_lshlrev_b32_e32 v86, 16, v87
	v_and_b32_e32 v87, 0xffff0000, v87
	v_pk_fma_f32 v[78:79], v[78:79], v[82:83], v[86:87]
	v_lshlrev_b32_e32 v82, 16, v84
	v_and_b32_e32 v83, 0xffff0000, v84
	v_lshlrev_b32_e32 v86, 16, v88
	v_and_b32_e32 v87, 0xffff0000, v88
	v_pk_fma_f32 v[82:83], v[72:73], v[82:83], v[86:87]
	v_lshlrev_b32_e32 v72, 16, v85
	v_and_b32_e32 v73, 0xffff0000, v85
	v_lshlrev_b32_e32 v84, 16, v89
	v_and_b32_e32 v85, 0xffff0000, v89
	v_pk_fma_f32 v[76:77], v[76:77], v[94:95], v[98:99]
	v_pk_fma_f32 v[84:85], v[74:75], v[72:73], v[84:85]
	v_cvt_pk_bf16_f32 v72, v76, v77
	v_cvt_pk_bf16_f32 v73, v78, v79
	v_cvt_pk_bf16_f32 v74, v82, v83
	v_cvt_pk_bf16_f32 v75, v84, v85
	v_lshl_add_u64 v[82:83], s[10:11], 0, v[90:91]
	global_store_dwordx4 v[82:83], v[72:75], off
	v_add_u32_e32 v200, 0xb0000, v144
	global_load_dwordx4 v[208:211], v200, s[8:9]
	global_load_dwordx4 v[240:243], v200, s[2:3]
	s_waitcnt vmcnt(21)
; __device__ __forceinline__ unsigned cvt_pk_bf16(float lo, float hi) { cvt_f32x2_t v = {lo, hi}; cvt_bf16x2_t b = __builtin_convertvector(v, cvt_bf16x2_t); return __builtin_bit_cast(unsigned, b); }
; __device__ __forceinline__ float bflo(unsigned w) { return __uint_as_float(w << 16); }
; __device__ __forceinline__ float bfhi(unsigned w) { return __uint_as_float(w & 0xffff0000u); }
;     __device__ __forceinline__ void operator()(const acc_t& acc, const pg8::Unit& u, int wr, int wc, int fr, int fq) const {
;         const int row0 = u.pm * 256 + wr * 64 + fr, col0 = u.pn * 256 + wc * 32 + 8 * fq;
; #pragma unroll
;         for (int ai = 0; ai < 2; ++ai)
; #pragma unroll
;             for (int m = 0; m < 4; ++m) { const size_t off = (size_t)(row0 + ai * 128 + m * 16) * D + col0;
; #pragma unroll
;                 for (int bj = 0; bj < 2; ++bj) { const f32x4 v0 = acc[ai][bj][m][0], v1 = acc[ai][bj][m][1];
;                     const u32x4 g = *(const u32x4*)(G + off + bj * 128);
;                     float o[8] = {bflo(g.x) * v0[0], bfhi(g.x) * v0[1], bflo(g.y) * v0[2], bfhi(g.y) * v0[3], bflo(g.z) * v1[0], bfhi(g.z) * v1[1], bflo(g.w) * v1[2], bfhi(g.w) * v1[3]};
;                     if (ADD) { const u32x4 t = *(const u32x4*)(T + off + bj * 128);
;                         o[0] += bflo(t.x); o[1] += bfhi(t.x); o[2] += bflo(t.y); o[3] += bfhi(t.y); o[4] += bflo(t.z); o[5] += bfhi(t.z); o[6] += bflo(t.w); o[7] += bfhi(t.w); }
;                     u32x4 w; w.x = cvt_pk_bf16(o[0], o[1]); w.y = cvt_pk_bf16(o[2], o[3]); w.z = cvt_pk_bf16(o[4], o[5]); w.w = cvt_pk_bf16(o[6], o[7]);
;                     *(u32x4*)(O + off + bj * 128) = w; }
;                 if (m & 1) asm volatile("" ::: "memory"); }
	s_nop 1
	v_mov_b64_e32 v[72:73], v[212:213]
	v_mov_b64_e32 v[74:75], v[214:215]
	s_nop 0
	v_mov_b64_e32 v[76:77], v[244:245]
	v_mov_b64_e32 v[78:79], v[246:247]
	v_lshlrev_b32_e32 v80, 16, v72
	v_and_b32_e32 v81, 0xffff0000, v72
	v_lshlrev_b32_e32 v84, 16, v76
	v_and_b32_e32 v85, 0xffff0000, v76
	v_lshlrev_b32_e32 v72, 16, v73
	v_and_b32_e32 v73, 0xffff0000, v73
	v_lshlrev_b32_e32 v76, 16, v77
	v_and_b32_e32 v77, 0xffff0000, v77
	v_pk_fma_f32 v[70:71], v[70:71], v[72:73], v[76:77]
	v_lshlrev_b32_e32 v72, 16, v74
	v_and_b32_e32 v73, 0xffff0000, v74
	v_lshlrev_b32_e32 v76, 16, v78
	v_and_b32_e32 v77, 0xffff0000, v78
	v_pk_fma_f32 v[72:73], v[64:65], v[72:73], v[76:77]
	v_lshlrev_b32_e32 v64, 16, v75
	v_and_b32_e32 v65, 0xffff0000, v75
	v_lshlrev_b32_e32 v74, 16, v79
	v_and_b32_e32 v75, 0xffff0000, v79
	v_pk_fma_f32 v[68:69], v[68:69], v[80:81], v[84:85]
	v_pk_fma_f32 v[74:75], v[66:67], v[64:65], v[74:75]
	v_cvt_pk_bf16_f32 v64, v68, v69
	v_cvt_pk_bf16_f32 v65, v70, v71
	v_cvt_pk_bf16_f32 v66, v72, v73
	v_cvt_pk_bf16_f32 v67, v74, v75
	global_store_dwordx4 v[82:83], v[64:67], off offset:256
	v_add_u32_e32 v200, 0xb0000, v144
	global_load_dwordx4 v[212:215], v200, s[8:9] offset:256
	global_load_dwordx4 v[244:247], v200, s[2:3] offset:256
	v_lshl_add_u64 v[74:75], v[144:145], 0, s[26:27]
	v_lshl_add_u64 v[76:77], s[2:3], 0, v[74:75]
	v_lshl_add_u64 v[64:65], s[8:9], 0, v[74:75]
	s_waitcnt vmcnt(21)
	s_nop 1
	v_mov_b64_e32 v[66:67], v[180:181]
	v_mov_b64_e32 v[68:69], v[182:183]
	v_mov_b64_e32 v[70:71], v[216:217]
	v_mov_b64_e32 v[72:73], v[218:219]
	s_mov_b64 s[26:27], 0x90000
	v_lshlrev_b32_e32 v78, 16, v66
	v_and_b32_e32 v79, 0xffff0000, v66
	v_lshlrev_b32_e32 v80, 16, v70
	v_and_b32_e32 v81, 0xffff0000, v70
	v_lshlrev_b32_e32 v66, 16, v67
	v_and_b32_e32 v67, 0xffff0000, v67
	v_lshlrev_b32_e32 v70, 16, v71
	v_and_b32_e32 v71, 0xffff0000, v71
	v_pk_fma_f32 v[62:63], v[62:63], v[66:67], v[70:71]
	v_lshlrev_b32_e32 v66, 16, v68
	v_and_b32_e32 v67, 0xffff0000, v68
	v_lshlrev_b32_e32 v70, 16, v72
	v_and_b32_e32 v71, 0xffff0000, v72
	v_pk_fma_f32 v[66:67], v[56:57], v[66:67], v[70:71]
	v_lshlrev_b32_e32 v56, 16, v69
	v_and_b32_e32 v57, 0xffff0000, v69
	v_lshlrev_b32_e32 v68, 16, v73
	v_and_b32_e32 v69, 0xffff0000, v73
	v_pk_fma_f32 v[60:61], v[60:61], v[78:79], v[80:81]
	v_pk_fma_f32 v[68:69], v[58:59], v[56:57], v[68:69]
	v_cvt_pk_bf16_f32 v56, v60, v61
	v_cvt_pk_bf16_f32 v57, v62, v63
	v_cvt_pk_bf16_f32 v58, v66, v67
	v_cvt_pk_bf16_f32 v59, v68, v69
	v_lshl_add_u64 v[66:67], s[10:11], 0, v[74:75]
	global_store_dwordx4 v[66:67], v[56:59], off
	s_waitcnt vmcnt(19)
	s_nop 1
	v_mov_b64_e32 v[56:57], v[184:185]
	v_mov_b64_e32 v[58:59], v[186:187]
	s_nop 0
	v_mov_b64_e32 v[60:61], v[220:221]
	v_mov_b64_e32 v[62:63], v[222:223]
	v_lshlrev_b32_e32 v64, 16, v56
	v_and_b32_e32 v65, 0xffff0000, v56
	v_lshlrev_b32_e32 v68, 16, v60
	v_and_b32_e32 v69, 0xffff0000, v60
	v_lshlrev_b32_e32 v56, 16, v57
	v_and_b32_e32 v57, 0xffff0000, v57
	v_lshlrev_b32_e32 v60, 16, v61
	v_and_b32_e32 v61, 0xffff0000, v61
	v_pk_fma_f32 v[54:55], v[54:55], v[56:57], v[60:61]
	v_lshlrev_b32_e32 v56, 16, v58
	v_and_b32_e32 v57, 0xffff0000, v58
	v_lshlrev_b32_e32 v60, 16, v62
	v_and_b32_e32 v61, 0xffff0000, v62
	v_pk_fma_f32 v[56:57], v[48:49], v[56:57], v[60:61]
	v_lshlrev_b32_e32 v48, 16, v59
	v_and_b32_e32 v49, 0xffff0000, v59
	v_lshlrev_b32_e32 v58, 16, v63
	v_and_b32_e32 v59, 0xffff0000, v63
	v_pk_fma_f32 v[52:53], v[52:53], v[64:65], v[68:69]
	v_pk_fma_f32 v[58:59], v[50:51], v[48:49], v[58:59]
	v_cvt_pk_bf16_f32 v48, v52, v53
	v_cvt_pk_bf16_f32 v49, v54, v55
	v_cvt_pk_bf16_f32 v50, v56, v57
	v_cvt_pk_bf16_f32 v51, v58, v59
	v_lshl_add_u64 v[58:59], v[144:145], 0, s[26:27]
	global_store_dwordx4 v[66:67], v[48:51], off offset:256
	v_lshl_add_u64 v[60:61], s[2:3], 0, v[58:59]
	s_waitcnt vmcnt(17)
	s_nop 1
	v_mov_b64_e32 v[54:55], v[224:225]
	v_mov_b64_e32 v[56:57], v[226:227]
	v_lshl_add_u64 v[48:49], s[8:9], 0, v[58:59]
	v_mov_b64_e32 v[50:51], v[188:189]
	v_mov_b64_e32 v[52:53], v[190:191]
	s_mov_b64 s[26:27], 0xa0000
	v_lshlrev_b32_e32 v64, 16, v54
	v_and_b32_e32 v65, 0xffff0000, v54
	v_lshlrev_b32_e32 v62, 16, v50
	v_and_b32_e32 v63, 0xffff0000, v50
	v_lshlrev_b32_e32 v50, 16, v51
	v_and_b32_e32 v51, 0xffff0000, v51
	v_lshlrev_b32_e32 v54, 16, v55
	v_and_b32_e32 v55, 0xffff0000, v55
	v_pk_fma_f32 v[46:47], v[46:47], v[50:51], v[54:55]
	v_lshlrev_b32_e32 v50, 16, v52
	v_and_b32_e32 v51, 0xffff0000, v52
	v_lshlrev_b32_e32 v54, 16, v56
	v_and_b32_e32 v55, 0xffff0000, v56
	v_pk_fma_f32 v[50:51], v[40:41], v[50:51], v[54:55]
	v_lshlrev_b32_e32 v40, 16, v53
	v_and_b32_e32 v41, 0xffff0000, v53
	v_lshlrev_b32_e32 v52, 16, v57
	v_and_b32_e32 v53, 0xffff0000, v57
	v_pk_fma_f32 v[44:45], v[44:45], v[62:63], v[64:65]
	v_pk_fma_f32 v[52:53], v[42:43], v[40:41], v[52:53]
	v_cvt_pk_bf16_f32 v40, v44, v45
	v_cvt_pk_bf16_f32 v41, v46, v47
	v_cvt_pk_bf16_f32 v42, v50, v51
	v_cvt_pk_bf16_f32 v43, v52, v53
	v_lshl_add_u64 v[50:51], s[10:11], 0, v[58:59]
	global_store_dwordx4 v[50:51], v[40:43], off
	s_waitcnt vmcnt(15)
; __device__ __forceinline__ unsigned cvt_pk_bf16(float lo, float hi) { cvt_f32x2_t v = {lo, hi}; cvt_bf16x2_t b = __builtin_convertvector(v, cvt_bf16x2_t); return __builtin_bit_cast(unsigned, b); }
; __device__ __forceinline__ float bflo(unsigned w) { return __uint_as_float(w << 16); }
; __device__ __forceinline__ float bfhi(unsigned w) { return __uint_as_float(w & 0xffff0000u); }
;     __device__ __forceinline__ void operator()(const acc_t& acc, const pg8::Unit& u, int wr, int wc, int fr, int fq) const {
;         const int row0 = u.pm * 256 + wr * 64 + fr, col0 = u.pn * 256 + wc * 32 + 8 * fq;
; #pragma unroll
;         for (int ai = 0; ai < 2; ++ai)
; #pragma unroll
;             for (int m = 0; m < 4; ++m) { const size_t off = (size_t)(row0 + ai * 128 + m * 16) * D + col0;
; #pragma unroll
;                 for (int bj = 0; bj < 2; ++bj) { const f32x4 v0 = acc[ai][bj][m][0], v1 = acc[ai][bj][m][1];
;                     const u32x4 g = *(const u32x4*)(G + off + bj * 128);
;                     float o[8] = {bflo(g.x) * v0[0], bfhi(g.x) * v0[1], bflo(g.y) * v0[2], bfhi(g.y) * v0[3], bflo(g.z) * v1[0], bfhi(g.z) * v1[1], bflo(g.w) * v1[2], bfhi(g.w) * v1[3]};
;                     if (ADD) { const u32x4 t = *(const u32x4*)(T + off + bj * 128);
;                         o[0] += bflo(t.x); o[1] += bfhi(t.x); o[2] += bflo(t.y); o[3] += bfhi(t.y); o[4] += bflo(t.z); o[5] += bfhi(t.z); o[6] += bflo(t.w); o[7] += bfhi(t.w); }
;                     u32x4 w; w.x = cvt_pk_bf16(o[0], o[1]); w.y = cvt_pk_bf16(o[2], o[3]); w.z = cvt_pk_bf16(o[4], o[5]); w.w = cvt_pk_bf16(o[6], o[7]);
;                     *(u32x4*)(O + off + bj * 128) = w; }
;                 if (m & 1) asm volatile("" ::: "memory"); }
	s_nop 1
	v_mov_b64_e32 v[40:41], v[192:193]
	v_mov_b64_e32 v[42:43], v[194:195]
	s_nop 0
	v_mov_b64_e32 v[44:45], v[228:229]
	v_mov_b64_e32 v[46:47], v[230:231]
	v_lshlrev_b32_e32 v48, 16, v40
	v_and_b32_e32 v49, 0xffff0000, v40
	v_lshlrev_b32_e32 v52, 16, v44
	v_and_b32_e32 v53, 0xffff0000, v44
	v_lshlrev_b32_e32 v40, 16, v41
	v_and_b32_e32 v41, 0xffff0000, v41
	v_lshlrev_b32_e32 v44, 16, v45
	v_and_b32_e32 v45, 0xffff0000, v45
	v_pk_fma_f32 v[38:39], v[38:39], v[40:41], v[44:45]
	v_lshlrev_b32_e32 v40, 16, v42
	v_and_b32_e32 v41, 0xffff0000, v42
	v_lshlrev_b32_e32 v44, 16, v46
	v_and_b32_e32 v45, 0xffff0000, v46
	v_pk_fma_f32 v[40:41], v[32:33], v[40:41], v[44:45]
	v_lshlrev_b32_e32 v32, 16, v43
	v_and_b32_e32 v33, 0xffff0000, v43
	v_lshlrev_b32_e32 v42, 16, v47
	v_and_b32_e32 v43, 0xffff0000, v47
	v_pk_fma_f32 v[36:37], v[36:37], v[48:49], v[52:53]
	v_pk_fma_f32 v[42:43], v[34:35], v[32:33], v[42:43]
	v_cvt_pk_bf16_f32 v32, v36, v37
	v_cvt_pk_bf16_f32 v33, v38, v39
	v_cvt_pk_bf16_f32 v34, v40, v41
	v_cvt_pk_bf16_f32 v35, v42, v43
	global_store_dwordx4 v[50:51], v[32:35], off offset:256
	v_lshl_add_u64 v[42:43], v[144:145], 0, s[26:27]
	v_lshl_add_u64 v[44:45], s[2:3], 0, v[42:43]
	v_lshl_add_u64 v[32:33], s[8:9], 0, v[42:43]
	s_waitcnt vmcnt(13)
	s_nop 1
	v_mov_b64_e32 v[34:35], v[196:197]
	v_mov_b64_e32 v[36:37], v[198:199]
	v_mov_b64_e32 v[38:39], v[232:233]
	v_mov_b64_e32 v[40:41], v[234:235]
	s_mov_b64 s[26:27], 0xb0000
	v_lshlrev_b32_e32 v46, 16, v34
	v_and_b32_e32 v47, 0xffff0000, v34
	v_lshlrev_b32_e32 v48, 16, v38
	v_and_b32_e32 v49, 0xffff0000, v38
	v_lshlrev_b32_e32 v34, 16, v35
	v_and_b32_e32 v35, 0xffff0000, v35
	v_lshlrev_b32_e32 v38, 16, v39
	v_and_b32_e32 v39, 0xffff0000, v39
	v_pk_fma_f32 v[30:31], v[30:31], v[34:35], v[38:39]
	v_lshlrev_b32_e32 v34, 16, v36
	v_and_b32_e32 v35, 0xffff0000, v36
	v_lshlrev_b32_e32 v38, 16, v40
	v_and_b32_e32 v39, 0xffff0000, v40
	v_pk_fma_f32 v[34:35], v[24:25], v[34:35], v[38:39]
	v_lshlrev_b32_e32 v24, 16, v37
	v_and_b32_e32 v25, 0xffff0000, v37
	v_lshlrev_b32_e32 v36, 16, v41
	v_and_b32_e32 v37, 0xffff0000, v41
	v_pk_fma_f32 v[28:29], v[28:29], v[46:47], v[48:49]
	v_pk_fma_f32 v[36:37], v[26:27], v[24:25], v[36:37]
	v_cvt_pk_bf16_f32 v24, v28, v29
	v_cvt_pk_bf16_f32 v25, v30, v31
	v_cvt_pk_bf16_f32 v26, v34, v35
	v_cvt_pk_bf16_f32 v27, v36, v37
	v_lshl_add_u64 v[34:35], s[10:11], 0, v[42:43]
	global_store_dwordx4 v[34:35], v[24:27], off
	s_waitcnt vmcnt(11)
	s_nop 1
	v_mov_b64_e32 v[24:25], v[204:205]
	v_mov_b64_e32 v[26:27], v[206:207]
	s_nop 0
	v_mov_b64_e32 v[28:29], v[236:237]
	v_mov_b64_e32 v[30:31], v[238:239]
	v_lshlrev_b32_e32 v32, 16, v24
	v_and_b32_e32 v33, 0xffff0000, v24
	v_lshlrev_b32_e32 v36, 16, v28
	v_and_b32_e32 v37, 0xffff0000, v28
	v_lshlrev_b32_e32 v24, 16, v25
	v_and_b32_e32 v25, 0xffff0000, v25
	v_lshlrev_b32_e32 v28, 16, v29
	v_and_b32_e32 v29, 0xffff0000, v29
	v_pk_fma_f32 v[22:23], v[22:23], v[24:25], v[28:29]
	v_lshlrev_b32_e32 v24, 16, v26
	v_and_b32_e32 v25, 0xffff0000, v26
	v_lshlrev_b32_e32 v28, 16, v30
	v_and_b32_e32 v29, 0xffff0000, v30
	v_pk_fma_f32 v[24:25], v[16:17], v[24:25], v[28:29]
	v_lshlrev_b32_e32 v16, 16, v27
	v_and_b32_e32 v17, 0xffff0000, v27
	v_lshlrev_b32_e32 v26, 16, v31
	v_and_b32_e32 v27, 0xffff0000, v31
	v_pk_fma_f32 v[20:21], v[20:21], v[32:33], v[36:37]
	v_pk_fma_f32 v[26:27], v[18:19], v[16:17], v[26:27]
	v_cvt_pk_bf16_f32 v16, v20, v21
	v_cvt_pk_bf16_f32 v17, v22, v23
	v_cvt_pk_bf16_f32 v18, v24, v25
	v_cvt_pk_bf16_f32 v19, v26, v27
	v_lshl_add_u64 v[26:27], v[144:145], 0, s[26:27]
	global_store_dwordx4 v[34:35], v[16:19], off offset:256
	v_lshl_add_u64 v[28:29], s[2:3], 0, v[26:27]
	s_waitcnt vmcnt(9)
	s_nop 1
	v_mov_b64_e32 v[22:23], v[240:241]
	v_mov_b64_e32 v[24:25], v[242:243]
	v_lshl_add_u64 v[16:17], s[8:9], 0, v[26:27]
	v_mov_b64_e32 v[18:19], v[208:209]
	v_mov_b64_e32 v[20:21], v[210:211]
	s_mov_b64 s[26:27], -1
	v_lshlrev_b32_e32 v32, 16, v22
	v_and_b32_e32 v33, 0xffff0000, v22
	v_lshlrev_b32_e32 v30, 16, v18
	v_and_b32_e32 v31, 0xffff0000, v18
	v_lshlrev_b32_e32 v18, 16, v19
	v_and_b32_e32 v19, 0xffff0000, v19
	v_lshlrev_b32_e32 v22, 16, v23
	v_and_b32_e32 v23, 0xffff0000, v23
	v_pk_fma_f32 v[14:15], v[14:15], v[18:19], v[22:23]
	v_lshlrev_b32_e32 v18, 16, v20
	v_and_b32_e32 v19, 0xffff0000, v20
	v_lshlrev_b32_e32 v22, 16, v24
	v_and_b32_e32 v23, 0xffff0000, v24
	v_pk_fma_f32 v[8:9], v[8:9], v[18:19], v[22:23]
	v_lshlrev_b32_e32 v18, 16, v21
	v_and_b32_e32 v19, 0xffff0000, v21
	v_lshlrev_b32_e32 v20, 16, v25
	v_and_b32_e32 v21, 0xffff0000, v25
	v_pk_fma_f32 v[12:13], v[12:13], v[30:31], v[32:33]
	v_pk_fma_f32 v[18:19], v[10:11], v[18:19], v[20:21]
	v_cvt_pk_bf16_f32 v10, v12, v13
	v_cvt_pk_bf16_f32 v11, v14, v15
	v_cvt_pk_bf16_f32 v12, v8, v9
	v_cvt_pk_bf16_f32 v13, v18, v19
	v_lshl_add_u64 v[8:9], s[10:11], 0, v[26:27]
	global_store_dwordx4 v[8:9], v[10:13], off
	s_waitcnt vmcnt(7)
	s_nop 1
	v_mov_b64_e32 v[10:11], v[212:213]
	v_mov_b64_e32 v[12:13], v[214:215]
	s_nop 0
	v_mov_b64_e32 v[14:15], v[244:245]
	v_mov_b64_e32 v[16:17], v[246:247]
	v_lshlrev_b32_e32 v18, 16, v10
	v_and_b32_e32 v19, 0xffff0000, v10
	v_lshlrev_b32_e32 v20, 16, v14
	v_and_b32_e32 v21, 0xffff0000, v14
	v_lshlrev_b32_e32 v10, 16, v11
	v_and_b32_e32 v11, 0xffff0000, v11
	v_lshlrev_b32_e32 v14, 16, v15
	v_and_b32_e32 v15, 0xffff0000, v15
	v_pk_fma_f32 v[6:7], v[6:7], v[10:11], v[14:15]
	v_lshlrev_b32_e32 v10, 16, v12
	v_and_b32_e32 v11, 0xffff0000, v12
	v_lshlrev_b32_e32 v14, 16, v16
	v_and_b32_e32 v15, 0xffff0000, v16
	v_pk_fma_f32 v[10:11], v[0:1], v[10:11], v[14:15]
	v_lshlrev_b32_e32 v0, 16, v13
	v_and_b32_e32 v1, 0xffff0000, v13
	v_lshlrev_b32_e32 v12, 16, v17
	v_and_b32_e32 v13, 0xffff0000, v17
	v_pk_fma_f32 v[4:5], v[4:5], v[18:19], v[20:21]
	v_pk_fma_f32 v[12:13], v[2:3], v[0:1], v[12:13]
	v_cvt_pk_bf16_f32 v0, v4, v5
	v_cvt_pk_bf16_f32 v1, v6, v7
	v_cvt_pk_bf16_f32 v2, v10, v11
	v_cvt_pk_bf16_f32 v3, v12, v13
	global_store_dwordx4 v[8:9], v[0:3], off offset:256
	s_cbranch_vccnz .LBB0_624
	s_andn2_b64 vcc, exec, s[12:13]
	s_cbranch_vccnz .LBB0_623
	s_barrier
	s_branch .LBB0_623
